# attention loop unrolled x4: static LDS ring offsets (no per-iteration address VALU), SGPR-base LDS-DMA pointers advanced by SALU, s_nop 5 dropped
# speedup vs baseline: 1.0302x; 1.0261x over previous
; #define AT_ADV() do { kg[0] += 64 * 1024; kg[1] += 64 * 1024; vg[0] += 64; vg[1] += 64; } while (0)
; __device__ __forceinline__ void attn_unit(unsigned char* ws, const float* sub_g, LAS unsigned char* lds, int h, int qb, float negM, float lam) {
;     ...
;     const bf16_t* Qp = (const bf16_t*)(ws + WS_Q); const bf16_t* Kp = (const bf16_t*)(ws + WS_K); const bf16_t* VTp = (const bf16_t*)(ws + WS_VT);
;     bf16x8 qf[4];
;     {
;         const bf16_t* qp = Qp + (size_t)(qrow0 + r32) * 1024 + (h * 2 + map) * 64 + 8 * hi;
; #pragma unroll
;         for (int d0 = 0; d0 < 4; ++d0) qf[d0] = *(const bf16x8*)(qp + 16 * d0);
;     }
;     const bf16_t* kg[2]; const bf16_t* vg[2];
; #pragma unroll
;     for (int i = 0; i < 2; ++i) {
;         const int g = 2 * wid + i;
;         const int kr = 4 * g + (lane >> 4), kc = (lane & 15) ^ (kr & 15);
;         kg[i] = Kp + (size_t)kr * 1024 + h * 128 + kc * 8;
;         const int vr = 8 * g + (lane >> 3), vc = (lane & 7) ^ ((vr >> 1) & 7);
;         vg[i] = VTp + (size_t)(h * 128 + vr) * NTOK + vc * 8;
;     }
;     const unsigned dmaoff = (unsigned)wid * 2048u;
;     ...
;     int kad[4], vad[4];
; #pragma unroll
;     for (int d0 = 0; d0 < 4; ++d0) kad[d0] = r32 * 256 + (((map * 8 + 2 * d0 + hi) ^ (r32 & 15)) << 4);
; #pragma unroll
;     for (int j = 0; j < 4; ++j) vad[j] = AT_KBYTES + r32 * 128 + (((2 * j + hi) ^ ((r32 >> 1) & 7)) << 4);
;     ...
;     f32x16 o[4];
; #pragma unroll
;     for (int b = 0; b < 4; ++b)
; #pragma unroll
;         for (int r = 0; r < 16; ++r) o[b][r] = 0.f;
;     f32x16 negm;
; #pragma unroll
;     for (int r = 0; r < 16; ++r) negm[r] = negM;
;     float l0 = 0.f, l1 = 0.f;
;     AT_DMA(0); AT_ADV();
;     asm volatile("s_waitcnt vmcnt(0)" ::: "memory");
;     __builtin_amdgcn_s_barrier();
;     AT_DMA(AT_BUF); AT_ADV();
;     f32x16 pa, pb;
;     {
;         f32x16 s0 = negm, s1 = negm;
; #pragma unroll
;         for (int d0 = 0; d0 < 4; ++d0) { s0 = __builtin_amdgcn_mfma_f32_32x32x16_bf16(KFR(0, d0, 0), qf[d0], s0, 0, 0, 0); s1 = __builtin_amdgcn_mfma_f32_32x32x16_bf16(KFR(0, d0, 1), qf[d0], s1, 0, 0, 0); }
; #pragma unroll
;         for (int r = 0; r < 16; ++r) { pa[r] = __builtin_amdgcn_exp2f(s0[r]); pb[r] = __builtin_amdgcn_exp2f(s1[r]); }
;     }
;     asm volatile("s_waitcnt vmcnt(0) lgkmcnt(0)" ::: "memory");
;     __builtin_amdgcn_s_barrier();
.LBB0_830:
	v_readfirstlane_b32 s25, v220
	s_bfe_u32 s29, s25, 0x20006
	s_lshl_b32 s8, s20, 4
	s_and_b32 s8, s8, 0xffffff80
	s_lshl_b32 s21, s29, 5
	s_or_b32 s21, s21, s8
	s_lshr_b32 s28, s25, 8
	v_or_b32_e32 v16, s21, v148
	s_lshl_b32 s8, s20, 7
	v_ashrrev_i32_e32 v17, 31, v16
	s_and_b32 s24, s8, 0x380
	s_lshl_b32 s8, s28, 6
	v_lshlrev_b64 v[16:17], 11, v[16:17]
	s_add_i32 s8, s8, s24
	v_lshl_add_u64 v[16:17], s[4:5], 0, v[16:17]
	s_lshl_b32 s8, s8, 1
	v_lshl_add_u64 v[16:17], v[16:17], 0, s[8:9]
	v_lshlrev_b32_e32 v130, 1, v128
	v_lshl_add_u64 v[16:17], v[16:17], 0, v[130:131]
	global_load_dwordx4 v[112:115], v[16:17], off
	global_load_dwordx4 v[116:119], v[16:17], off offset:32
	global_load_dwordx4 v[120:123], v[16:17], off offset:64
	global_load_dwordx4 v[124:127], v[16:17], off offset:96
	s_lshr_b32 s33, s25, 6
	s_lshr_b32 s8, s25, 5
	s_lshl_b32 s30, s24, 1
	s_add_u32 s30, s3, s30
	s_addc_u32 s31, s18, 0
	s_lshl_b32 s34, s33, 3
	v_or_b32_e32 v130, s34, v150
	v_bitop3_b32 v18, s34, v220, v150 bitop3:0x36
	v_lshlrev_b64 v[16:17], 11, v[130:131]
	v_lshlrev_b32_e32 v18, 4, v18
	v_lshl_add_u64 v[16:17], s[30:31], 0, v[16:17]
	v_and_b32_e32 v130, 0xf0, v18
	v_lshl_add_u64 v[56:57], v[16:17], 0, v[130:131]
	v_lshl_or_b32 v16, s33, 4, v151
	v_lshrrev_b32_e32 v17, 1, v151
	v_xor_b32_e32 v20, v17, v220
	v_add_u32_e32 v18, s24, v16
	v_mov_b64_e32 v[16:17], s[6:7]
	v_mad_u64_u32 v[18:19], s[34:35], v18, s19, v[16:17]
	v_lshlrev_b32_e32 v20, 4, v20
	s_or_b32 s8, s8, 1
	v_and_b32_e32 v130, 0x70, v20
	s_lshl_b32 s34, s8, 2
	v_lshl_add_u64 v[58:59], v[18:19], 0, v[130:131]
	v_or_b32_e32 v130, s34, v150
	v_bitop3_b32 v20, s34, v220, v150 bitop3:0x36
	v_lshlrev_b64 v[18:19], 11, v[130:131]
	v_lshlrev_b32_e32 v20, 4, v20
	v_lshl_add_u64 v[18:19], s[30:31], 0, v[18:19]
	v_and_b32_e32 v130, 0xf0, v20
	v_lshl_add_u64 v[60:61], v[18:19], 0, v[130:131]
	v_lshl_or_b32 v18, s8, 3, v151
	v_lshrrev_b32_e32 v19, 1, v18
	v_add_u32_e32 v18, s24, v18
	s_lshl_b32 s8, s33, 11
	v_mad_u64_u32 v[16:17], s[30:31], v18, s19, v[16:17]
	s_add_i32 s8, s8, 0
	v_xor_b32_e32 v19, v19, v220
	s_add_i32 s31, s8, 0x4000
	s_mov_b32 m0, s8
	v_lshlrev_b32_e32 v18, 4, v19
	global_load_lds_dwordx4 v[56:57], off
	s_mov_b32 m0, s31
	v_and_b32_e32 v130, 0x70, v18
	global_load_lds_dwordx4 v[58:59], off
	s_add_i32 m0, s8, 0x400
	v_lshl_add_u64 v[62:63], v[16:17], 0, v[130:131]
	global_load_lds_dwordx4 v[60:61], off
	s_add_i32 m0, s8, 0x4400
	v_lshl_add_u64 v[16:17], v[56:57], 0, s[10:11]
	global_load_lds_dwordx4 v[62:63], off
	s_add_i32 m0, s8, 0x8000
	s_add_i32 s31, s8, 0xc000
	v_lshl_add_u64 v[20:21], v[58:59], 0, s[12:13]
	s_waitcnt vmcnt(0)
	s_barrier
	global_load_lds_dwordx4 v[16:17], off
	s_mov_b32 m0, s31
	v_lshl_add_u64 v[18:19], v[60:61], 0, s[10:11]
	global_load_lds_dwordx4 v[20:21], off
	s_add_i32 m0, s8, 0x8400
	v_lshl_add_u64 v[22:23], v[62:63], 0, s[12:13]
	global_load_lds_dwordx4 v[18:19], off
	s_add_i32 m0, s8, 0xc400
	s_lshl_b32 s30, s28, 3
	global_load_lds_dwordx4 v[22:23], off
	v_bitop3_b32 v24, s30, v153, v149 bitop3:0x36
	v_lshl_add_u32 v198, v24, 4, v154
	ds_read_b128 v[32:35], v198
	ds_read_b128 v[48:51], v198 offset:8192
	s_waitcnt lgkmcnt(0)
	v_mfma_f32_32x32x16_bf16 v[16:31], v[32:35], v[112:115], v[0:15]
	v_or_b32_e32 v64, s30, v149
	v_bitop3_b32 v32, v64, v153, 2 bitop3:0x36
	v_lshlrev_b32_e32 v65, 4, v32
	v_add_u32_e32 v52, v154, v65
	v_add_u32_e32 v200, v65, v152
	s_mov_b32 s30, 0x8000
	v_lshl_add_u64 v[140:141], v[56:57], 0, s[14:15]
	v_mfma_f32_32x32x16_bf16 v[32:47], v[48:51], v[112:115], v[0:15]
	ds_read_b128 v[48:51], v52
	ds_read_b128 v[52:55], v52 offset:8192
	v_lshl_add_u64 v[142:143], v[60:61], 0, s[14:15]
	v_lshl_add_u64 v[144:145], v[58:59], 0, s[16:17]
	v_lshl_add_u64 v[146:147], v[62:63], 0, s[16:17]
	s_mov_b32 s31, 0x18000
	s_add_i32 m0, s8, 0x10000
	s_nop 0
	global_load_lds_dwordx4 v[140:141], off
	s_add_i32 m0, s8, 0x14000
	s_nop 0
	global_load_lds_dwordx4 v[144:145], off
	s_add_i32 m0, s8, 0x10400
	s_nop 0
	global_load_lds_dwordx4 v[142:143], off
	s_add_i32 m0, s8, 0x14400
	s_nop 0
	global_load_lds_dwordx4 v[146:147], off
	v_lshl_add_u64 v[140:141], v[140:141], 0, s[10:11]
	v_lshl_add_u64 v[142:143], v[142:143], 0, s[10:11]
	v_lshl_add_u64 v[144:145], v[144:145], 0, s[12:13]
	v_lshl_add_u64 v[146:147], v[146:147], 0, s[12:13]
	s_mov_b32 s98, s3
	s_mov_b32 s99, s18
	s_mov_b64 s[100:101], s[6:7]
	v_subrev_u32_e32 v140, s3, v140
	v_subrev_u32_e32 v142, s3, v142
	v_subrev_u32_e32 v144, s6, v144
	v_subrev_u32_e32 v146, s6, v146
	v_mov_b32_e32 v216, 0
	v_mov_b32_e32 v199, 0
	s_waitcnt lgkmcnt(1)
	v_mfma_f32_32x32x16_bf16 v[16:31], v[48:51], v[116:119], v[16:31]
	v_bitop3_b32 v48, v64, v153, 4 bitop3:0x36
	v_lshlrev_b32_e32 v66, 4, v48
	v_add_u32_e32 v201, v66, v152
	s_mov_b32 s36, 0
	s_mov_b32 s33, 1
	v_mov_b32_e32 v56, v131
	v_mov_b32_e32 v57, v131
	s_waitcnt lgkmcnt(0)
	v_mfma_f32_32x32x16_bf16 v[32:47], v[52:55], v[116:119], v[32:47]
	v_add_u32_e32 v52, v154, v66
	ds_read_b128 v[48:51], v52
	ds_read_b128 v[52:55], v52 offset:8192
	v_mov_b32_e32 v58, v131
	v_mov_b32_e32 v59, v131
	v_mov_b32_e32 v60, v131
	v_mov_b32_e32 v61, v131
	v_mov_b32_e32 v62, v131
	s_waitcnt lgkmcnt(1)
	v_mfma_f32_32x32x16_bf16 v[16:31], v[48:51], v[120:123], v[16:31]
	v_bitop3_b32 v48, v64, v153, 6 bitop3:0x36
	v_lshlrev_b32_e32 v64, 4, v48
	v_add_u32_e32 v202, v64, v152
	v_mov_b32_e32 v63, v131
	v_mov_b32_e32 v65, v131
	v_mov_b32_e32 v66, v131
	v_mov_b32_e32 v67, v131
	s_waitcnt lgkmcnt(0)
	v_mfma_f32_32x32x16_bf16 v[32:47], v[52:55], v[120:123], v[32:47]
	v_add_u32_e32 v52, v154, v64
	ds_read_b128 v[48:51], v52
	ds_read_b128 v[52:55], v52 offset:8192
	s_waitcnt vmcnt(4) lgkmcnt(0)
; #define AT_ADV() do { kg[0] += 64 * 1024; kg[1] += 64 * 1024; vg[0] += 64; vg[1] += 64; } while (0)
; __device__ __forceinline__ void attn_unit(unsigned char* ws, const float* sub_g, LAS unsigned char* lds, int h, int qb, float negM, float lam) {
;     ...
;     f32x16 o[4];
; #pragma unroll
;     for (int b = 0; b < 4; ++b)
; #pragma unroll
;         for (int r = 0; r < 16; ++r) o[b][r] = 0.f;
;     f32x16 negm;
; #pragma unroll
;     for (int r = 0; r < 16; ++r) negm[r] = negM;
;     float l0 = 0.f, l1 = 0.f;
;     AT_DMA(0); AT_ADV();
;     asm volatile("s_waitcnt vmcnt(0)" ::: "memory");
;     __builtin_amdgcn_s_barrier();
;     AT_DMA(AT_BUF); AT_ADV();
;     f32x16 pa, pb;
;     {
;         f32x16 s0 = negm, s1 = negm;
; #pragma unroll
;         for (int d0 = 0; d0 < 4; ++d0) { s0 = __builtin_amdgcn_mfma_f32_32x32x16_bf16(KFR(0, d0, 0), qf[d0], s0, 0, 0, 0); s1 = __builtin_amdgcn_mfma_f32_32x32x16_bf16(KFR(0, d0, 1), qf[d0], s1, 0, 0, 0); }
; #pragma unroll
;         for (int r = 0; r < 16; ++r) { pa[r] = __builtin_amdgcn_exp2f(s0[r]); pb[r] = __builtin_amdgcn_exp2f(s1[r]); }
;     }
;     asm volatile("s_waitcnt vmcnt(0) lgkmcnt(0)" ::: "memory");
;     __builtin_amdgcn_s_barrier();
;     int bV = 0, bK = AT_BUF, bW = 2 * AT_BUF;
;     ...
;         f32x16 s0, s1;
;         bf16x8 F0 = FLOAD(0), F1 = FLOAD(1), F2;
;         SB();
;         F2 = FLOAD(2); s0 = __builtin_amdgcn_mfma_f32_32x32x16_bf16(F0, qf[0], negm, 0, 0, 0); ADD4(pa, 0); pw[0][0] = cvtpk(pa[0], pa[1]); SB();
;         F0 = FLOAD(3); s1 = __builtin_amdgcn_mfma_f32_32x32x16_bf16(F1, qf[0], negm, 0, 0, 0); ADD4(pa, 4); pw[0][1] = cvtpk(pa[2], pa[3]); SB();
;         F1 = FLOAD(4); s0 = __builtin_amdgcn_mfma_f32_32x32x16_bf16(F2, qf[1], s0, 0, 0, 0); ADD4(pa, 8); pw[0][2] = cvtpk(pa[4], pa[5]); SB();
;         F2 = FLOAD(5); s1 = __builtin_amdgcn_mfma_f32_32x32x16_bf16(F0, qf[1], s1, 0, 0, 0); ADD4(pa, 12); pw[0][3] = cvtpk(pa[6], pa[7]); SB();
;         F0 = FLOAD(6); s0 = __builtin_amdgcn_mfma_f32_32x32x16_bf16(F1, qf[2], s0, 0, 0, 0); ADD4(pb, 0); pw[1][0] = cvtpk(pa[8], pa[9]); SB();
;         F1 = FLOAD(7); s1 = __builtin_amdgcn_mfma_f32_32x32x16_bf16(F2, qf[2], s1, 0, 0, 0); ADD4(pb, 4); pw[1][1] = cvtpk(pa[10], pa[11]); SB();
;         F2 = FLOAD(8); s0 = __builtin_amdgcn_mfma_f32_32x32x16_bf16(F0, qf[3], s0, 0, 0, 0); ADD4(pb, 8); pw[1][2] = cvtpk(pa[12], pa[13]); SB();
	v_mov_b32_e32 v64, 0
	v_mov_b32_e32 v68, v131
	v_mov_b32_e32 v69, v131
	s_waitcnt lgkmcnt(1)
	v_mfma_f32_32x32x16_bf16 v[16:31], v[48:51], v[124:127], v[16:31]
	v_mov_b32_e32 v48, 0
	v_mov_b32_e32 v49, v131
	v_mov_b32_e32 v50, v131
	v_mov_b32_e32 v51, v131
	v_mov_b32_e32 v70, v131
	v_mov_b32_e32 v71, v131
	v_mov_b32_e32 v72, v131
	s_waitcnt lgkmcnt(0)
	v_mfma_f32_32x32x16_bf16 v[32:47], v[52:55], v[124:127], v[32:47]
	s_nop 2
	v_exp_f32_e32 v217, v16
	v_exp_f32_e32 v219, v17
	v_exp_f32_e32 v218, v18
	v_exp_f32_e32 v222, v19
	v_exp_f32_e32 v211, v20
	v_exp_f32_e32 v215, v21
	v_exp_f32_e32 v209, v22
	s_nop 1
	v_exp_f32_e32 v130, v32
	v_exp_f32_e32 v187, v33
	v_exp_f32_e32 v183, v34
	v_exp_f32_e32 v190, v35
	v_exp_f32_e32 v184, v36
	v_exp_f32_e32 v192, v37
	v_exp_f32_e32 v185, v38
	v_exp_f32_e32 v213, v23
	v_exp_f32_e32 v193, v39
	v_exp_f32_e32 v210, v24
	v_exp_f32_e32 v188, v40
	v_exp_f32_e32 v214, v25
	v_exp_f32_e32 v196, v41
	v_exp_f32_e32 v207, v26
	v_exp_f32_e32 v191, v42
	v_exp_f32_e32 v208, v27
	v_exp_f32_e32 v197, v43
	v_exp_f32_e32 v205, v28
	v_exp_f32_e32 v189, v44
	v_exp_f32_e32 v206, v29
	v_exp_f32_e32 v194, v45
	v_exp_f32_e32 v204, v30
	v_exp_f32_e32 v186, v46
	v_exp_f32_e32 v203, v31
	v_exp_f32_e32 v195, v47
	v_mov_b32_e32 v16, 0
	v_mov_b32_e32 v17, v131
	v_mov_b32_e32 v18, v131
	v_mov_b32_e32 v19, v131
	v_mov_b32_e32 v20, v131
	v_mov_b32_e32 v21, v131
	v_mov_b32_e32 v22, v131
	v_mov_b32_e32 v23, v131
	v_mov_b32_e32 v24, v131
	v_mov_b32_e32 v25, v131
	v_mov_b32_e32 v26, v131
	v_mov_b32_e32 v27, v131
	v_mov_b32_e32 v28, v131
	v_mov_b32_e32 v29, v131
	v_mov_b32_e32 v30, v131
	v_mov_b32_e32 v31, v131
	v_mov_b32_e32 v32, 0
	v_mov_b32_e32 v33, v131
	v_mov_b32_e32 v34, v131
	v_mov_b32_e32 v35, v131
	v_mov_b32_e32 v36, v131
	v_mov_b32_e32 v37, v131
	v_mov_b32_e32 v38, v131
	v_mov_b32_e32 v39, v131
	v_mov_b32_e32 v40, v131
	v_mov_b32_e32 v41, v131
	v_mov_b32_e32 v42, v131
	v_mov_b32_e32 v43, v131
	v_mov_b32_e32 v44, v131
	v_mov_b32_e32 v45, v131
	v_mov_b32_e32 v46, v131
	v_mov_b32_e32 v47, v131
	v_mov_b32_e32 v52, v131
	v_mov_b32_e32 v53, v131
	v_mov_b32_e32 v54, v131
	v_mov_b32_e32 v55, v131
	v_mov_b32_e32 v73, v131
	v_mov_b32_e32 v74, v131
	v_mov_b32_e32 v75, v131
	v_mov_b32_e32 v76, v131
	v_mov_b32_e32 v77, v131
	v_mov_b32_e32 v78, v131
	v_mov_b32_e32 v79, v131
	v_add_u32_e32 v247, 0x10000, v198
	v_add_u32_e32 v248, 0x10000, v200
	v_add_u32_e32 v249, 0x10000, v201
	v_add_u32_e32 v250, 0x10000, v202
	v_add_u32_e32 v251, 0x10000, v178
	v_add_u32_e32 v252, 0x10000, v179
	v_add_u32_e32 v253, 0x10000, v180
	v_add_u32_e32 v254, 0x10000, v181
	s_barrier
	s_branch .Lattn_c1
.Lattn_c1:
	ds_read_b128 v[80:83], v198 offset:32768
	ds_read_b128 v[224:227], v198 offset:40960
	ds_read_b128 v[228:231], v200 offset:32768
	v_add_f32_e32 v85, v216, v217
	v_add_f32_e32 v86, v199, v219
	s_waitcnt lgkmcnt(2)
	v_mfma_f32_32x32x16_bf16 v[96:111], v[80:83], v[112:115], v[0:15]
	v_add_f32_e32 v85, v85, v218
	v_add_f32_e32 v80, v86, v222
	v_cvt_pk_bf16_f32 v232, v217, v219
	ds_read_b128 v[236:239], v200 offset:40960
	v_add_f32_e32 v81, v85, v211
	v_add_f32_e32 v80, v80, v215
	v_cvt_pk_bf16_f32 v233, v218, v222
	v_add_f32_e32 v199, v81, v209
	v_add_f32_e32 v223, v80, v213
	s_waitcnt lgkmcnt(2)
	v_mfma_f32_32x32x16_bf16 v[80:95], v[224:227], v[112:115], v[0:15]
	ds_read_b128 v[216:219], v201 offset:32768
	v_add_f32_e32 v199, v199, v210
	v_add_f32_e32 v223, v223, v214
	s_waitcnt lgkmcnt(2)
	v_mfma_f32_32x32x16_bf16 v[96:111], v[228:231], v[116:119], v[96:111]
	v_add_f32_e32 v199, v199, v207
	v_add_f32_e32 v226, v223, v208
	v_cvt_pk_bf16_f32 v234, v211, v215
	ds_read_b128 v[222:225], v201 offset:40960
	v_add_f32_e32 v199, v199, v205
	v_add_f32_e32 v211, v226, v206
	v_cvt_pk_bf16_f32 v235, v209, v213
	v_add_f32_e32 v199, v199, v204
	v_add_f32_e32 v211, v211, v203
	s_waitcnt lgkmcnt(2)
	v_mfma_f32_32x32x16_bf16 v[80:95], v[236:239], v[116:119], v[80:95]
	ds_read_b128 v[226:229], v202 offset:32768
	v_add_f32_e32 v199, v199, v130
	v_add_f32_e32 v211, v211, v187
	s_waitcnt lgkmcnt(2)
	v_mfma_f32_32x32x16_bf16 v[96:111], v[216:219], v[120:123], v[96:111]
	v_add_f32_e32 v199, v199, v183
	v_add_f32_e32 v211, v211, v190
	v_cvt_pk_bf16_f32 v236, v210, v214
	ds_read_b128 v[240:243], v202 offset:40960
	v_add_f32_e32 v199, v199, v184
	v_add_f32_e32 v209, v211, v192
	v_cvt_pk_bf16_f32 v237, v207, v208
	v_add_f32_e32 v199, v199, v185
	v_add_f32_e32 v213, v209, v193
	s_waitcnt lgkmcnt(2)
	v_mfma_f32_32x32x16_bf16 v[80:95], v[222:225], v[120:123], v[80:95]
	ds_read_b128 v[208:211], v178 offset:16384
	v_add_f32_e32 v199, v199, v188
	v_add_f32_e32 v207, v213, v196
	s_waitcnt lgkmcnt(2)
	v_mfma_f32_32x32x16_bf16 v[96:111], v[226:229], v[124:127], v[96:111]
	v_add_f32_e32 v199, v199, v191
	v_add_f32_e32 v207, v207, v197
	v_cvt_pk_bf16_f32 v238, v205, v206
	ds_read_b128 v[224:227], v178 offset:20480
	v_add_f32_e32 v199, v199, v189
	v_add_f32_e32 v205, v207, v194
	v_cvt_pk_bf16_f32 v239, v204, v203
	v_add_f32_e32 v216, v199, v186
	v_add_f32_e32 v199, v205, v195
	s_waitcnt lgkmcnt(2)
	v_mfma_f32_32x32x16_bf16 v[80:95], v[240:243], v[124:127], v[80:95]
	s_waitcnt vmcnt(0)
	s_barrier
; #define SB() __builtin_amdgcn_sched_barrier(0)
; #define FLOAD(i) (*(const LAS bf16x8*)(lds + FADDR(i)))
; __device__ __forceinline__ void attn_unit(unsigned char* ws, const float* sub_g, LAS unsigned char* lds, int h, int qb, float negM, float lam) {
;     ...
;         F2 = FLOAD(2); s0 = __builtin_amdgcn_mfma_f32_32x32x16_bf16(F0, qf[0], negm, 0, 0, 0); ADD4(pa, 0); pw[0][0] = cvtpk(pa[0], pa[1]); SB();
;         F0 = FLOAD(3); s1 = __builtin_amdgcn_mfma_f32_32x32x16_bf16(F1, qf[0], negm, 0, 0, 0); ADD4(pa, 4); pw[0][1] = cvtpk(pa[2], pa[3]); SB();
;         F1 = FLOAD(4); s0 = __builtin_amdgcn_mfma_f32_32x32x16_bf16(F2, qf[1], s0, 0, 0, 0); ADD4(pa, 8); pw[0][2] = cvtpk(pa[4], pa[5]); SB();
;         F2 = FLOAD(5); s1 = __builtin_amdgcn_mfma_f32_32x32x16_bf16(F0, qf[1], s1, 0, 0, 0); ADD4(pa, 12); pw[0][3] = cvtpk(pa[6], pa[7]); SB();
;         F0 = FLOAD(6); s0 = __builtin_amdgcn_mfma_f32_32x32x16_bf16(F1, qf[2], s0, 0, 0, 0); ADD4(pb, 0); pw[1][0] = cvtpk(pa[8], pa[9]); SB();
;         F1 = FLOAD(7); s1 = __builtin_amdgcn_mfma_f32_32x32x16_bf16(F2, qf[2], s1, 0, 0, 0); ADD4(pb, 4); pw[1][1] = cvtpk(pa[10], pa[11]); SB();
;         F2 = FLOAD(8); s0 = __builtin_amdgcn_mfma_f32_32x32x16_bf16(F0, qf[3], s0, 0, 0, 0); ADD4(pb, 8); pw[1][2] = cvtpk(pa[12], pa[13]); SB();
;         F0 = FLOAD(9); s1 = __builtin_amdgcn_mfma_f32_32x32x16_bf16(F1, qf[3], s1, 0, 0, 0); ADD4(pb, 12); pw[1][3] = cvtpk(pa[14], pa[15]); SB();
;         F1 = FLOAD(10); o[0] = __builtin_amdgcn_mfma_f32_32x32x16_bf16(F2, __builtin_bit_cast(bf16x8, pw[0]), o[0], 0, 0, 0); pw[2][0] = cvtpk(pb[0], pb[1]); EXP2(s0, pa, 0); SB();
;         F2 = FLOAD(11); o[1] = __builtin_amdgcn_mfma_f32_32x32x16_bf16(F0, __builtin_bit_cast(bf16x8, pw[0]), o[1], 0, 0, 0); pw[2][1] = cvtpk(pb[2], pb[3]); EXP2(s0, pa, 2); SB();
;         F0 = FLOAD(12); o[2] = __builtin_amdgcn_mfma_f32_32x32x16_bf16(F1, __builtin_bit_cast(bf16x8, pw[0]), o[2], 0, 0, 0); pw[2][2] = cvtpk(pb[4], pb[5]); EXP2(s0, pa, 4); SB();
;         F1 = FLOAD(13); o[3] = __builtin_amdgcn_mfma_f32_32x32x16_bf16(F2, __builtin_bit_cast(bf16x8, pw[0]), o[3], 0, 0, 0); pw[2][3] = cvtpk(pb[6], pb[7]); EXP2(s0, pa, 6); SB();
;         F2 = FLOAD(14); o[0] = __builtin_amdgcn_mfma_f32_32x32x16_bf16(F0, __builtin_bit_cast(bf16x8, pw[1]), o[0], 0, 0, 0); pw[3][0] = cvtpk(pb[8], pb[9]); EXP2(s0, pa, 8); SB();
	s_waitcnt lgkmcnt(1)
	v_mfma_f32_32x32x16_bf16 v[64:79], v[208:211], v[232:235], v[64:79]
	s_add_i32 m0, s8, 0x18000
	ds_read_b128 v[204:207], v178 offset:24576
	global_load_lds_dwordx4 v140, s[98:99]
	v_exp_f32_e32 v217, v96
	v_exp_f32_e32 v219, v97
	v_cvt_pk_bf16_f32 v228, v130, v187
	s_waitcnt lgkmcnt(1)
	v_mfma_f32_32x32x16_bf16 v[48:63], v[224:227], v[232:235], v[48:63]
	ds_read_b128 v[240:243], v178 offset:28672
	v_exp_f32_e32 v218, v98
	v_exp_f32_e32 v222, v99
	v_cvt_pk_bf16_f32 v229, v183, v190
	s_waitcnt lgkmcnt(1)
	v_mfma_f32_32x32x16_bf16 v[32:47], v[204:207], v[232:235], v[32:47]
	s_add_i32 m0, m0, 0x4000
	ds_read_b128 v[96:99], v179 offset:16384
	global_load_lds_dwordx4 v144, s[100:101]
	v_exp_f32_e32 v211, v100
	v_exp_f32_e32 v215, v101
	v_cvt_pk_bf16_f32 v230, v184, v192
	s_waitcnt lgkmcnt(1)
	v_mfma_f32_32x32x16_bf16 v[16:31], v[240:243], v[232:235], v[16:31]
	ds_read_b128 v[224:227], v179 offset:20480
	v_exp_f32_e32 v209, v102
	v_exp_f32_e32 v213, v103
	v_cvt_pk_bf16_f32 v231, v185, v193
	s_waitcnt lgkmcnt(1)
	v_mfma_f32_32x32x16_bf16 v[64:79], v[96:99], v[236:239], v[64:79]
	s_add_i32 m0, m0, 0xffffc400
	ds_read_b128 v[100:103], v179 offset:24576
	global_load_lds_dwordx4 v142, s[98:99]
	v_exp_f32_e32 v210, v104
	v_exp_f32_e32 v214, v105
	v_cvt_pk_bf16_f32 v232, v188, v196
	s_waitcnt lgkmcnt(1)
	v_mfma_f32_32x32x16_bf16 v[48:63], v[224:227], v[236:239], v[48:63]
	ds_read_b128 v[96:99], v179 offset:28672
	v_exp_f32_e32 v207, v106
	v_exp_f32_e32 v208, v107
	v_cvt_pk_bf16_f32 v233, v191, v197
	s_waitcnt lgkmcnt(1)
	v_mfma_f32_32x32x16_bf16 v[32:47], v[100:103], v[236:239], v[32:47]
	s_add_i32 m0, m0, 0x4000
	ds_read_b128 v[104:107], v180 offset:16384
	global_load_lds_dwordx4 v146, s[100:101]
	s_add_u32 s98, s98, 0x20000
	s_addc_u32 s99, s99, 0
	s_add_u32 s100, s100, 0x80
	s_addc_u32 s101, s101, 0
	v_exp_f32_e32 v205, v108
	v_exp_f32_e32 v206, v109
	v_cvt_pk_bf16_f32 v234, v189, v194
	s_waitcnt lgkmcnt(1)
	v_mfma_f32_32x32x16_bf16 v[16:31], v[96:99], v[236:239], v[16:31]
	ds_read_b128 v[100:103], v180 offset:20480
	v_exp_f32_e32 v204, v110
	v_exp_f32_e32 v203, v111
	v_cvt_pk_bf16_f32 v235, v186, v195
	s_waitcnt lgkmcnt(1)
	v_mfma_f32_32x32x16_bf16 v[64:79], v[104:107], v[228:231], v[64:79]
	ds_read_b128 v[96:99], v180 offset:24576
	v_exp_f32_e32 v130, v80
	v_exp_f32_e32 v187, v81
	s_waitcnt lgkmcnt(1)
	v_mfma_f32_32x32x16_bf16 v[48:63], v[100:103], v[228:231], v[48:63]
	ds_read_b128 v[104:107], v180 offset:28672
	v_exp_f32_e32 v183, v82
	v_exp_f32_e32 v190, v83
	s_waitcnt lgkmcnt(1)
	v_mfma_f32_32x32x16_bf16 v[32:47], v[96:99], v[228:231], v[32:47]
	ds_read_b128 v[80:83], v181 offset:16384
	v_exp_f32_e32 v184, v84
	v_exp_f32_e32 v192, v85
	s_waitcnt lgkmcnt(1)
	v_mfma_f32_32x32x16_bf16 v[16:31], v[104:107], v[228:231], v[16:31]
	ds_read_b128 v[96:99], v181 offset:20480
	v_exp_f32_e32 v185, v86
	v_exp_f32_e32 v193, v87
	s_waitcnt lgkmcnt(1)
	v_mfma_f32_32x32x16_bf16 v[64:79], v[80:83], v[232:235], v[64:79]
	ds_read_b128 v[84:87], v181 offset:24576
	v_exp_f32_e32 v188, v88
	v_exp_f32_e32 v196, v89
	s_waitcnt lgkmcnt(1)
	v_mfma_f32_32x32x16_bf16 v[48:63], v[96:99], v[232:235], v[48:63]
	ds_read_b128 v[80:83], v181 offset:28672
	v_exp_f32_e32 v191, v90
	v_exp_f32_e32 v197, v91
	s_waitcnt lgkmcnt(1)
	v_mfma_f32_32x32x16_bf16 v[32:47], v[84:87], v[232:235], v[32:47]
	v_exp_f32_e32 v189, v92
	v_exp_f32_e32 v194, v93
	s_waitcnt lgkmcnt(0)
	v_mfma_f32_32x32x16_bf16 v[16:31], v[80:83], v[232:235], v[16:31]
	v_exp_f32_e32 v186, v94
	v_exp_f32_e32 v195, v95
	s_waitcnt lgkmcnt(0)
	s_add_i32 s33, s33, 1
.Lattn_c2:
	ds_read_b128 v[80:83], v247
	ds_read_b128 v[224:227], v247 offset:8192
	ds_read_b128 v[228:231], v248
	v_add_f32_e32 v85, v216, v217
	v_add_f32_e32 v86, v199, v219
	s_waitcnt lgkmcnt(2)
	v_mfma_f32_32x32x16_bf16 v[96:111], v[80:83], v[112:115], v[0:15]
	v_add_f32_e32 v85, v85, v218
	v_add_f32_e32 v80, v86, v222
	v_cvt_pk_bf16_f32 v232, v217, v219
	ds_read_b128 v[236:239], v248 offset:8192
	v_add_f32_e32 v81, v85, v211
	v_add_f32_e32 v80, v80, v215
	v_cvt_pk_bf16_f32 v233, v218, v222
	v_add_f32_e32 v199, v81, v209
	v_add_f32_e32 v223, v80, v213
	s_waitcnt lgkmcnt(2)
	v_mfma_f32_32x32x16_bf16 v[80:95], v[224:227], v[112:115], v[0:15]
	ds_read_b128 v[216:219], v249
	v_add_f32_e32 v199, v199, v210
	v_add_f32_e32 v223, v223, v214
	s_waitcnt lgkmcnt(2)
	v_mfma_f32_32x32x16_bf16 v[96:111], v[228:231], v[116:119], v[96:111]
	v_add_f32_e32 v199, v199, v207
	v_add_f32_e32 v226, v223, v208
	v_cvt_pk_bf16_f32 v234, v211, v215
	ds_read_b128 v[222:225], v249 offset:8192
	v_add_f32_e32 v199, v199, v205
	v_add_f32_e32 v211, v226, v206
	v_cvt_pk_bf16_f32 v235, v209, v213
	v_add_f32_e32 v199, v199, v204
	v_add_f32_e32 v211, v211, v203
	s_waitcnt lgkmcnt(2)
	v_mfma_f32_32x32x16_bf16 v[80:95], v[236:239], v[116:119], v[80:95]
	ds_read_b128 v[226:229], v250
	v_add_f32_e32 v199, v199, v130
	v_add_f32_e32 v211, v211, v187
	s_waitcnt lgkmcnt(2)
	v_mfma_f32_32x32x16_bf16 v[96:111], v[216:219], v[120:123], v[96:111]
	v_add_f32_e32 v199, v199, v183
	v_add_f32_e32 v211, v211, v190
	v_cvt_pk_bf16_f32 v236, v210, v214
	ds_read_b128 v[240:243], v250 offset:8192
	v_add_f32_e32 v199, v199, v184
	v_add_f32_e32 v209, v211, v192
	v_cvt_pk_bf16_f32 v237, v207, v208
	v_add_f32_e32 v199, v199, v185
	v_add_f32_e32 v213, v209, v193
	s_waitcnt lgkmcnt(2)
	v_mfma_f32_32x32x16_bf16 v[80:95], v[222:225], v[120:123], v[80:95]
	ds_read_b128 v[208:211], v178 offset:49152
	v_add_f32_e32 v199, v199, v188
	v_add_f32_e32 v207, v213, v196
	s_waitcnt lgkmcnt(2)
	v_mfma_f32_32x32x16_bf16 v[96:111], v[226:229], v[124:127], v[96:111]
	v_add_f32_e32 v199, v199, v191
	v_add_f32_e32 v207, v207, v197
	v_cvt_pk_bf16_f32 v238, v205, v206
	ds_read_b128 v[224:227], v178 offset:53248
	v_add_f32_e32 v199, v199, v189
	v_add_f32_e32 v205, v207, v194
	v_cvt_pk_bf16_f32 v239, v204, v203
	v_add_f32_e32 v216, v199, v186
	v_add_f32_e32 v199, v205, v195
	s_waitcnt lgkmcnt(2)
	v_mfma_f32_32x32x16_bf16 v[80:95], v[240:243], v[124:127], v[80:95]
	s_waitcnt vmcnt(0)
	s_barrier
; #define SB() __builtin_amdgcn_sched_barrier(0)
; #define FLOAD(i) (*(const LAS bf16x8*)(lds + FADDR(i)))
; __device__ __forceinline__ void attn_unit(unsigned char* ws, const float* sub_g, LAS unsigned char* lds, int h, int qb, float negM, float lam) {
;     ...
;         F2 = FLOAD(2); s0 = __builtin_amdgcn_mfma_f32_32x32x16_bf16(F0, qf[0], negm, 0, 0, 0); ADD4(pa, 0); pw[0][0] = cvtpk(pa[0], pa[1]); SB();
;         F0 = FLOAD(3); s1 = __builtin_amdgcn_mfma_f32_32x32x16_bf16(F1, qf[0], negm, 0, 0, 0); ADD4(pa, 4); pw[0][1] = cvtpk(pa[2], pa[3]); SB();
;         F1 = FLOAD(4); s0 = __builtin_amdgcn_mfma_f32_32x32x16_bf16(F2, qf[1], s0, 0, 0, 0); ADD4(pa, 8); pw[0][2] = cvtpk(pa[4], pa[5]); SB();
;         F2 = FLOAD(5); s1 = __builtin_amdgcn_mfma_f32_32x32x16_bf16(F0, qf[1], s1, 0, 0, 0); ADD4(pa, 12); pw[0][3] = cvtpk(pa[6], pa[7]); SB();
;         F0 = FLOAD(6); s0 = __builtin_amdgcn_mfma_f32_32x32x16_bf16(F1, qf[2], s0, 0, 0, 0); ADD4(pb, 0); pw[1][0] = cvtpk(pa[8], pa[9]); SB();
;         F1 = FLOAD(7); s1 = __builtin_amdgcn_mfma_f32_32x32x16_bf16(F2, qf[2], s1, 0, 0, 0); ADD4(pb, 4); pw[1][1] = cvtpk(pa[10], pa[11]); SB();
;         F2 = FLOAD(8); s0 = __builtin_amdgcn_mfma_f32_32x32x16_bf16(F0, qf[3], s0, 0, 0, 0); ADD4(pb, 8); pw[1][2] = cvtpk(pa[12], pa[13]); SB();
;         F0 = FLOAD(9); s1 = __builtin_amdgcn_mfma_f32_32x32x16_bf16(F1, qf[3], s1, 0, 0, 0); ADD4(pb, 12); pw[1][3] = cvtpk(pa[14], pa[15]); SB();
;         F1 = FLOAD(10); o[0] = __builtin_amdgcn_mfma_f32_32x32x16_bf16(F2, __builtin_bit_cast(bf16x8, pw[0]), o[0], 0, 0, 0); pw[2][0] = cvtpk(pb[0], pb[1]); EXP2(s0, pa, 0); SB();
;         F2 = FLOAD(11); o[1] = __builtin_amdgcn_mfma_f32_32x32x16_bf16(F0, __builtin_bit_cast(bf16x8, pw[0]), o[1], 0, 0, 0); pw[2][1] = cvtpk(pb[2], pb[3]); EXP2(s0, pa, 2); SB();
;         F0 = FLOAD(12); o[2] = __builtin_amdgcn_mfma_f32_32x32x16_bf16(F1, __builtin_bit_cast(bf16x8, pw[0]), o[2], 0, 0, 0); pw[2][2] = cvtpk(pb[4], pb[5]); EXP2(s0, pa, 4); SB();
;         F1 = FLOAD(13); o[3] = __builtin_amdgcn_mfma_f32_32x32x16_bf16(F2, __builtin_bit_cast(bf16x8, pw[0]), o[3], 0, 0, 0); pw[2][3] = cvtpk(pb[6], pb[7]); EXP2(s0, pa, 6); SB();
;         F2 = FLOAD(14); o[0] = __builtin_amdgcn_mfma_f32_32x32x16_bf16(F0, __builtin_bit_cast(bf16x8, pw[1]), o[0], 0, 0, 0); pw[3][0] = cvtpk(pb[8], pb[9]); EXP2(s0, pa, 8); SB();
	s_waitcnt lgkmcnt(1)
	v_mfma_f32_32x32x16_bf16 v[64:79], v[208:211], v[232:235], v[64:79]
	s_add_i32 m0, s8, 0x0
	ds_read_b128 v[204:207], v178 offset:57344
	global_load_lds_dwordx4 v140, s[98:99]
	v_exp_f32_e32 v217, v96
	v_exp_f32_e32 v219, v97
	v_cvt_pk_bf16_f32 v228, v130, v187
	s_waitcnt lgkmcnt(1)
	v_mfma_f32_32x32x16_bf16 v[48:63], v[224:227], v[232:235], v[48:63]
	ds_read_b128 v[240:243], v178 offset:61440
	v_exp_f32_e32 v218, v98
	v_exp_f32_e32 v222, v99
	v_cvt_pk_bf16_f32 v229, v183, v190
	s_waitcnt lgkmcnt(1)
	v_mfma_f32_32x32x16_bf16 v[32:47], v[204:207], v[232:235], v[32:47]
	s_add_i32 m0, m0, 0x4000
	ds_read_b128 v[96:99], v179 offset:49152
	global_load_lds_dwordx4 v144, s[100:101]
	v_exp_f32_e32 v211, v100
	v_exp_f32_e32 v215, v101
	v_cvt_pk_bf16_f32 v230, v184, v192
	s_waitcnt lgkmcnt(1)
	v_mfma_f32_32x32x16_bf16 v[16:31], v[240:243], v[232:235], v[16:31]
	ds_read_b128 v[224:227], v179 offset:53248
	v_exp_f32_e32 v209, v102
	v_exp_f32_e32 v213, v103
	v_cvt_pk_bf16_f32 v231, v185, v193
	s_waitcnt lgkmcnt(1)
	v_mfma_f32_32x32x16_bf16 v[64:79], v[96:99], v[236:239], v[64:79]
	s_add_i32 m0, m0, 0xffffc400
	ds_read_b128 v[100:103], v179 offset:57344
	global_load_lds_dwordx4 v142, s[98:99]
	v_exp_f32_e32 v210, v104
	v_exp_f32_e32 v214, v105
	v_cvt_pk_bf16_f32 v232, v188, v196
	s_waitcnt lgkmcnt(1)
	v_mfma_f32_32x32x16_bf16 v[48:63], v[224:227], v[236:239], v[48:63]
	ds_read_b128 v[96:99], v179 offset:61440
	v_exp_f32_e32 v207, v106
	v_exp_f32_e32 v208, v107
	v_cvt_pk_bf16_f32 v233, v191, v197
	s_waitcnt lgkmcnt(1)
	v_mfma_f32_32x32x16_bf16 v[32:47], v[100:103], v[236:239], v[32:47]
	s_add_i32 m0, m0, 0x4000
	ds_read_b128 v[104:107], v180 offset:49152
	global_load_lds_dwordx4 v146, s[100:101]
	s_add_u32 s98, s98, 0x20000
	s_addc_u32 s99, s99, 0
	s_add_u32 s100, s100, 0x80
	s_addc_u32 s101, s101, 0
	v_exp_f32_e32 v205, v108
	v_exp_f32_e32 v206, v109
	v_cvt_pk_bf16_f32 v234, v189, v194
	s_waitcnt lgkmcnt(1)
	v_mfma_f32_32x32x16_bf16 v[16:31], v[96:99], v[236:239], v[16:31]
	ds_read_b128 v[100:103], v180 offset:53248
	v_exp_f32_e32 v204, v110
	v_exp_f32_e32 v203, v111
	v_cvt_pk_bf16_f32 v235, v186, v195
	s_waitcnt lgkmcnt(1)
	v_mfma_f32_32x32x16_bf16 v[64:79], v[104:107], v[228:231], v[64:79]
	ds_read_b128 v[96:99], v180 offset:57344
	v_exp_f32_e32 v130, v80
	v_exp_f32_e32 v187, v81
	s_waitcnt lgkmcnt(1)
	v_mfma_f32_32x32x16_bf16 v[48:63], v[100:103], v[228:231], v[48:63]
	ds_read_b128 v[104:107], v180 offset:61440
	v_exp_f32_e32 v183, v82
	v_exp_f32_e32 v190, v83
	s_waitcnt lgkmcnt(1)
	v_mfma_f32_32x32x16_bf16 v[32:47], v[96:99], v[228:231], v[32:47]
	ds_read_b128 v[80:83], v181 offset:49152
	v_exp_f32_e32 v184, v84
	v_exp_f32_e32 v192, v85
	s_waitcnt lgkmcnt(1)
	v_mfma_f32_32x32x16_bf16 v[16:31], v[104:107], v[228:231], v[16:31]
	ds_read_b128 v[96:99], v181 offset:53248
	v_exp_f32_e32 v185, v86
	v_exp_f32_e32 v193, v87
	s_waitcnt lgkmcnt(1)
	v_mfma_f32_32x32x16_bf16 v[64:79], v[80:83], v[232:235], v[64:79]
	ds_read_b128 v[84:87], v181 offset:57344
	v_exp_f32_e32 v188, v88
	v_exp_f32_e32 v196, v89
	s_waitcnt lgkmcnt(1)
	v_mfma_f32_32x32x16_bf16 v[48:63], v[96:99], v[232:235], v[48:63]
	ds_read_b128 v[80:83], v181 offset:61440
	v_exp_f32_e32 v191, v90
	v_exp_f32_e32 v197, v91
	s_waitcnt lgkmcnt(1)
	v_mfma_f32_32x32x16_bf16 v[32:47], v[84:87], v[232:235], v[32:47]
	v_exp_f32_e32 v189, v92
	v_exp_f32_e32 v194, v93
	s_waitcnt lgkmcnt(0)
	v_mfma_f32_32x32x16_bf16 v[16:31], v[80:83], v[232:235], v[16:31]
	v_exp_f32_e32 v186, v94
	v_exp_f32_e32 v195, v95
	s_waitcnt lgkmcnt(0)
	s_add_i32 s33, s33, 1
.Lattn_c3:
	ds_read_b128 v[80:83], v247 offset:32768
	ds_read_b128 v[224:227], v247 offset:40960
	ds_read_b128 v[228:231], v248 offset:32768
	v_add_f32_e32 v85, v216, v217
	v_add_f32_e32 v86, v199, v219
	s_waitcnt lgkmcnt(2)
	v_mfma_f32_32x32x16_bf16 v[96:111], v[80:83], v[112:115], v[0:15]
	v_add_f32_e32 v85, v85, v218
	v_add_f32_e32 v80, v86, v222
	v_cvt_pk_bf16_f32 v232, v217, v219
	ds_read_b128 v[236:239], v248 offset:40960
	v_add_f32_e32 v81, v85, v211
	v_add_f32_e32 v80, v80, v215
	v_cvt_pk_bf16_f32 v233, v218, v222
	v_add_f32_e32 v199, v81, v209
	v_add_f32_e32 v223, v80, v213
	s_waitcnt lgkmcnt(2)
	v_mfma_f32_32x32x16_bf16 v[80:95], v[224:227], v[112:115], v[0:15]
	ds_read_b128 v[216:219], v249 offset:32768
	v_add_f32_e32 v199, v199, v210
	v_add_f32_e32 v223, v223, v214
	s_waitcnt lgkmcnt(2)
	v_mfma_f32_32x32x16_bf16 v[96:111], v[228:231], v[116:119], v[96:111]
	v_add_f32_e32 v199, v199, v207
	v_add_f32_e32 v226, v223, v208
	v_cvt_pk_bf16_f32 v234, v211, v215
	ds_read_b128 v[222:225], v249 offset:40960
	v_add_f32_e32 v199, v199, v205
	v_add_f32_e32 v211, v226, v206
	v_cvt_pk_bf16_f32 v235, v209, v213
	v_add_f32_e32 v199, v199, v204
	v_add_f32_e32 v211, v211, v203
	s_waitcnt lgkmcnt(2)
	v_mfma_f32_32x32x16_bf16 v[80:95], v[236:239], v[116:119], v[80:95]
	ds_read_b128 v[226:229], v250 offset:32768
	v_add_f32_e32 v199, v199, v130
	v_add_f32_e32 v211, v211, v187
	s_waitcnt lgkmcnt(2)
	v_mfma_f32_32x32x16_bf16 v[96:111], v[216:219], v[120:123], v[96:111]
	v_add_f32_e32 v199, v199, v183
	v_add_f32_e32 v211, v211, v190
	v_cvt_pk_bf16_f32 v236, v210, v214
	ds_read_b128 v[240:243], v250 offset:40960
	v_add_f32_e32 v199, v199, v184
	v_add_f32_e32 v209, v211, v192
	v_cvt_pk_bf16_f32 v237, v207, v208
	v_add_f32_e32 v199, v199, v185
	v_add_f32_e32 v213, v209, v193
	s_waitcnt lgkmcnt(2)
	v_mfma_f32_32x32x16_bf16 v[80:95], v[222:225], v[120:123], v[80:95]
	ds_read_b128 v[208:211], v251 offset:16384
	v_add_f32_e32 v199, v199, v188
	v_add_f32_e32 v207, v213, v196
	s_waitcnt lgkmcnt(2)
	v_mfma_f32_32x32x16_bf16 v[96:111], v[226:229], v[124:127], v[96:111]
	v_add_f32_e32 v199, v199, v191
	v_add_f32_e32 v207, v207, v197
	v_cvt_pk_bf16_f32 v238, v205, v206
	ds_read_b128 v[224:227], v251 offset:20480
	v_add_f32_e32 v199, v199, v189
	v_add_f32_e32 v205, v207, v194
	v_cvt_pk_bf16_f32 v239, v204, v203
	v_add_f32_e32 v216, v199, v186
	v_add_f32_e32 v199, v205, v195
	s_waitcnt lgkmcnt(2)
	v_mfma_f32_32x32x16_bf16 v[80:95], v[240:243], v[124:127], v[80:95]
	s_waitcnt vmcnt(0)
	s_barrier
; __device__ __forceinline__ void attn_unit(unsigned char* ws, const float* sub_g, LAS unsigned char* lds, int h, int qb, float negM, float lam) {
;     ...
;         F1 = FLOAD(10); o[0] = __builtin_amdgcn_mfma_f32_32x32x16_bf16(F2, __builtin_bit_cast(bf16x8, pw[0]), o[0], 0, 0, 0); pw[2][0] = cvtpk(pb[0], pb[1]); EXP2(s0, pa, 0); SB();
;         F2 = FLOAD(11); o[1] = __builtin_amdgcn_mfma_f32_32x32x16_bf16(F0, __builtin_bit_cast(bf16x8, pw[0]), o[1], 0, 0, 0); pw[2][1] = cvtpk(pb[2], pb[3]); EXP2(s0, pa, 2); SB();
;         F0 = FLOAD(12); o[2] = __builtin_amdgcn_mfma_f32_32x32x16_bf16(F1, __builtin_bit_cast(bf16x8, pw[0]), o[2], 0, 0, 0); pw[2][2] = cvtpk(pb[4], pb[5]); EXP2(s0, pa, 4); SB();
;         F1 = FLOAD(13); o[3] = __builtin_amdgcn_mfma_f32_32x32x16_bf16(F2, __builtin_bit_cast(bf16x8, pw[0]), o[3], 0, 0, 0); pw[2][3] = cvtpk(pb[6], pb[7]); EXP2(s0, pa, 6); SB();
;         F2 = FLOAD(14); o[0] = __builtin_amdgcn_mfma_f32_32x32x16_bf16(F0, __builtin_bit_cast(bf16x8, pw[1]), o[0], 0, 0, 0); pw[3][0] = cvtpk(pb[8], pb[9]); EXP2(s0, pa, 8); SB();
;         F0 = FLOAD(15); o[1] = __builtin_amdgcn_mfma_f32_32x32x16_bf16(F1, __builtin_bit_cast(bf16x8, pw[1]), o[1], 0, 0, 0); pw[3][1] = cvtpk(pb[10], pb[11]); EXP2(s0, pa, 10); SB();
;         F1 = FLOAD(16); o[2] = __builtin_amdgcn_mfma_f32_32x32x16_bf16(F2, __builtin_bit_cast(bf16x8, pw[1]), o[2], 0, 0, 0); pw[3][2] = cvtpk(pb[12], pb[13]); EXP2(s0, pa, 12); SB();
;         F2 = FLOAD(17); o[3] = __builtin_amdgcn_mfma_f32_32x32x16_bf16(F0, __builtin_bit_cast(bf16x8, pw[1]), o[3], 0, 0, 0); pw[3][3] = cvtpk(pb[14], pb[15]); EXP2(s0, pa, 14); SB();
;         F0 = FLOAD(18); o[0] = __builtin_amdgcn_mfma_f32_32x32x16_bf16(F1, __builtin_bit_cast(bf16x8, pw[2]), o[0], 0, 0, 0); EXP2(s1, pb, 0); SB();
;         F1 = FLOAD(19); o[1] = __builtin_amdgcn_mfma_f32_32x32x16_bf16(F2, __builtin_bit_cast(bf16x8, pw[2]), o[1], 0, 0, 0); EXP2(s1, pb, 2); SB();
;         F2 = FLOAD(20); o[2] = __builtin_amdgcn_mfma_f32_32x32x16_bf16(F0, __builtin_bit_cast(bf16x8, pw[2]), o[2], 0, 0, 0); EXP2(s1, pb, 4); SB();
;         F0 = FLOAD(21); o[3] = __builtin_amdgcn_mfma_f32_32x32x16_bf16(F1, __builtin_bit_cast(bf16x8, pw[2]), o[3], 0, 0, 0); EXP2(s1, pb, 6); SB();
;         F1 = FLOAD(22); o[0] = __builtin_amdgcn_mfma_f32_32x32x16_bf16(F2, __builtin_bit_cast(bf16x8, pw[3]), o[0], 0, 0, 0); EXP2(s1, pb, 8); SB();
	s_waitcnt lgkmcnt(1)
	v_mfma_f32_32x32x16_bf16 v[64:79], v[208:211], v[232:235], v[64:79]
	s_add_i32 m0, s8, 0x8000
	ds_read_b128 v[204:207], v251 offset:24576
	global_load_lds_dwordx4 v140, s[98:99]
	v_exp_f32_e32 v217, v96
	v_exp_f32_e32 v219, v97
	v_cvt_pk_bf16_f32 v228, v130, v187
	s_waitcnt lgkmcnt(1)
	v_mfma_f32_32x32x16_bf16 v[48:63], v[224:227], v[232:235], v[48:63]
	ds_read_b128 v[240:243], v251 offset:28672
	v_exp_f32_e32 v218, v98
	v_exp_f32_e32 v222, v99
	v_cvt_pk_bf16_f32 v229, v183, v190
	s_waitcnt lgkmcnt(1)
	v_mfma_f32_32x32x16_bf16 v[32:47], v[204:207], v[232:235], v[32:47]
	s_add_i32 m0, m0, 0x4000
	ds_read_b128 v[96:99], v252 offset:16384
	global_load_lds_dwordx4 v144, s[100:101]
	v_exp_f32_e32 v211, v100
	v_exp_f32_e32 v215, v101
	v_cvt_pk_bf16_f32 v230, v184, v192
	s_waitcnt lgkmcnt(1)
	v_mfma_f32_32x32x16_bf16 v[16:31], v[240:243], v[232:235], v[16:31]
	ds_read_b128 v[224:227], v252 offset:20480
	v_exp_f32_e32 v209, v102
	v_exp_f32_e32 v213, v103
	v_cvt_pk_bf16_f32 v231, v185, v193
	s_waitcnt lgkmcnt(1)
	v_mfma_f32_32x32x16_bf16 v[64:79], v[96:99], v[236:239], v[64:79]
	s_add_i32 m0, m0, 0xffffc400
	ds_read_b128 v[100:103], v252 offset:24576
	global_load_lds_dwordx4 v142, s[98:99]
	v_exp_f32_e32 v210, v104
	v_exp_f32_e32 v214, v105
	v_cvt_pk_bf16_f32 v232, v188, v196
	s_waitcnt lgkmcnt(1)
	v_mfma_f32_32x32x16_bf16 v[48:63], v[224:227], v[236:239], v[48:63]
	ds_read_b128 v[96:99], v252 offset:28672
	v_exp_f32_e32 v207, v106
	v_exp_f32_e32 v208, v107
	v_cvt_pk_bf16_f32 v233, v191, v197
	s_waitcnt lgkmcnt(1)
	v_mfma_f32_32x32x16_bf16 v[32:47], v[100:103], v[236:239], v[32:47]
	s_add_i32 m0, m0, 0x4000
	ds_read_b128 v[104:107], v253 offset:16384
	global_load_lds_dwordx4 v146, s[100:101]
	s_add_u32 s98, s98, 0x20000
	s_addc_u32 s99, s99, 0
	s_add_u32 s100, s100, 0x80
	s_addc_u32 s101, s101, 0
	v_exp_f32_e32 v205, v108
	v_exp_f32_e32 v206, v109
	v_cvt_pk_bf16_f32 v234, v189, v194
	s_waitcnt lgkmcnt(1)
	v_mfma_f32_32x32x16_bf16 v[16:31], v[96:99], v[236:239], v[16:31]
	ds_read_b128 v[100:103], v253 offset:20480
	v_exp_f32_e32 v204, v110
	v_exp_f32_e32 v203, v111
	v_cvt_pk_bf16_f32 v235, v186, v195
	s_waitcnt lgkmcnt(1)
	v_mfma_f32_32x32x16_bf16 v[64:79], v[104:107], v[228:231], v[64:79]
	ds_read_b128 v[96:99], v253 offset:24576
	v_exp_f32_e32 v130, v80
	v_exp_f32_e32 v187, v81
	s_waitcnt lgkmcnt(1)
	v_mfma_f32_32x32x16_bf16 v[48:63], v[100:103], v[228:231], v[48:63]
	ds_read_b128 v[104:107], v253 offset:28672
	v_exp_f32_e32 v183, v82
	v_exp_f32_e32 v190, v83
	s_waitcnt lgkmcnt(1)
	v_mfma_f32_32x32x16_bf16 v[32:47], v[96:99], v[228:231], v[32:47]
	ds_read_b128 v[80:83], v254 offset:16384
	v_exp_f32_e32 v184, v84
	v_exp_f32_e32 v192, v85
	s_waitcnt lgkmcnt(1)
	v_mfma_f32_32x32x16_bf16 v[16:31], v[104:107], v[228:231], v[16:31]
	ds_read_b128 v[96:99], v254 offset:20480
	v_exp_f32_e32 v185, v86
	v_exp_f32_e32 v193, v87
	s_waitcnt lgkmcnt(1)
	v_mfma_f32_32x32x16_bf16 v[64:79], v[80:83], v[232:235], v[64:79]
	ds_read_b128 v[84:87], v254 offset:24576
	v_exp_f32_e32 v188, v88
	v_exp_f32_e32 v196, v89
	s_waitcnt lgkmcnt(1)
	v_mfma_f32_32x32x16_bf16 v[48:63], v[96:99], v[232:235], v[48:63]
	ds_read_b128 v[80:83], v254 offset:28672
	v_exp_f32_e32 v191, v90
	v_exp_f32_e32 v197, v91
	s_waitcnt lgkmcnt(1)
	v_mfma_f32_32x32x16_bf16 v[32:47], v[84:87], v[232:235], v[32:47]
	v_exp_f32_e32 v189, v92
	v_exp_f32_e32 v194, v93
	s_waitcnt lgkmcnt(0)
	v_mfma_f32_32x32x16_bf16 v[16:31], v[80:83], v[232:235], v[16:31]
	v_exp_f32_e32 v186, v94
	v_exp_f32_e32 v195, v95
	s_waitcnt lgkmcnt(0)
	s_add_i32 s33, s33, 1
	s_cmpk_eq_i32 s33, 0x84
	s_cbranch_scc1 .Lattn_exit
; #define SB() __builtin_amdgcn_sched_barrier(0)
; __device__ __forceinline__ void attn_unit(unsigned char* ws, const float* sub_g, LAS unsigned char* lds, int h, int qb, float negM, float lam) {
;     ...
;         f32x16 s0, s1;
;         bf16x8 F0 = FLOAD(0), F1 = FLOAD(1), F2;
;         SB();
;         F2 = FLOAD(2); s0 = __builtin_amdgcn_mfma_f32_32x32x16_bf16(F0, qf[0], negm, 0, 0, 0); ADD4(pa, 0); pw[0][0] = cvtpk(pa[0], pa[1]); SB();
;         F0 = FLOAD(3); s1 = __builtin_amdgcn_mfma_f32_32x32x16_bf16(F1, qf[0], negm, 0, 0, 0); ADD4(pa, 4); pw[0][1] = cvtpk(pa[2], pa[3]); SB();
;         F1 = FLOAD(4); s0 = __builtin_amdgcn_mfma_f32_32x32x16_bf16(F2, qf[1], s0, 0, 0, 0); ADD4(pa, 8); pw[0][2] = cvtpk(pa[4], pa[5]); SB();
;         F2 = FLOAD(5); s1 = __builtin_amdgcn_mfma_f32_32x32x16_bf16(F0, qf[1], s1, 0, 0, 0); ADD4(pa, 12); pw[0][3] = cvtpk(pa[6], pa[7]); SB();
;         F0 = FLOAD(6); s0 = __builtin_amdgcn_mfma_f32_32x32x16_bf16(F1, qf[2], s0, 0, 0, 0); ADD4(pb, 0); pw[1][0] = cvtpk(pa[8], pa[9]); SB();
;         F1 = FLOAD(7); s1 = __builtin_amdgcn_mfma_f32_32x32x16_bf16(F2, qf[2], s1, 0, 0, 0); ADD4(pb, 4); pw[1][1] = cvtpk(pa[10], pa[11]); SB();
;         F2 = FLOAD(8); s0 = __builtin_amdgcn_mfma_f32_32x32x16_bf16(F0, qf[3], s0, 0, 0, 0); ADD4(pb, 8); pw[1][2] = cvtpk(pa[12], pa[13]); SB();
;         F0 = FLOAD(9); s1 = __builtin_amdgcn_mfma_f32_32x32x16_bf16(F1, qf[3], s1, 0, 0, 0); ADD4(pb, 12); pw[1][3] = cvtpk(pa[14], pa[15]); SB();
;         F1 = FLOAD(10); o[0] = __builtin_amdgcn_mfma_f32_32x32x16_bf16(F2, __builtin_bit_cast(bf16x8, pw[0]), o[0], 0, 0, 0); pw[2][0] = cvtpk(pb[0], pb[1]); EXP2(s0, pa, 0); SB();
;         F2 = FLOAD(11); o[1] = __builtin_amdgcn_mfma_f32_32x32x16_bf16(F0, __builtin_bit_cast(bf16x8, pw[0]), o[1], 0, 0, 0); pw[2][1] = cvtpk(pb[2], pb[3]); EXP2(s0, pa, 2); SB();
;         F0 = FLOAD(12); o[2] = __builtin_amdgcn_mfma_f32_32x32x16_bf16(F1, __builtin_bit_cast(bf16x8, pw[0]), o[2], 0, 0, 0); pw[2][2] = cvtpk(pb[4], pb[5]); EXP2(s0, pa, 4); SB();
;         F1 = FLOAD(13); o[3] = __builtin_amdgcn_mfma_f32_32x32x16_bf16(F2, __builtin_bit_cast(bf16x8, pw[0]), o[3], 0, 0, 0); pw[2][3] = cvtpk(pb[6], pb[7]); EXP2(s0, pa, 6); SB();
;         F2 = FLOAD(14); o[0] = __builtin_amdgcn_mfma_f32_32x32x16_bf16(F0, __builtin_bit_cast(bf16x8, pw[1]), o[0], 0, 0, 0); pw[3][0] = cvtpk(pb[8], pb[9]); EXP2(s0, pa, 8); SB();
.Lattn_c0:
	ds_read_b128 v[80:83], v198
	ds_read_b128 v[224:227], v198 offset:8192
	ds_read_b128 v[228:231], v200
	v_add_f32_e32 v85, v216, v217
	v_add_f32_e32 v86, v199, v219
	s_waitcnt lgkmcnt(2)
	v_mfma_f32_32x32x16_bf16 v[96:111], v[80:83], v[112:115], v[0:15]
	v_add_f32_e32 v85, v85, v218
	v_add_f32_e32 v80, v86, v222
	v_cvt_pk_bf16_f32 v232, v217, v219
	ds_read_b128 v[236:239], v200 offset:8192
	v_add_f32_e32 v81, v85, v211
	v_add_f32_e32 v80, v80, v215
	v_cvt_pk_bf16_f32 v233, v218, v222
	v_add_f32_e32 v199, v81, v209
	v_add_f32_e32 v223, v80, v213
	s_waitcnt lgkmcnt(2)
	v_mfma_f32_32x32x16_bf16 v[80:95], v[224:227], v[112:115], v[0:15]
	ds_read_b128 v[216:219], v201
	v_add_f32_e32 v199, v199, v210
	v_add_f32_e32 v223, v223, v214
	s_waitcnt lgkmcnt(2)
	v_mfma_f32_32x32x16_bf16 v[96:111], v[228:231], v[116:119], v[96:111]
	v_add_f32_e32 v199, v199, v207
	v_add_f32_e32 v226, v223, v208
	v_cvt_pk_bf16_f32 v234, v211, v215
	ds_read_b128 v[222:225], v201 offset:8192
	v_add_f32_e32 v199, v199, v205
	v_add_f32_e32 v211, v226, v206
	v_cvt_pk_bf16_f32 v235, v209, v213
	v_add_f32_e32 v199, v199, v204
	v_add_f32_e32 v211, v211, v203
	s_waitcnt lgkmcnt(2)
	v_mfma_f32_32x32x16_bf16 v[80:95], v[236:239], v[116:119], v[80:95]
	ds_read_b128 v[226:229], v202
	v_add_f32_e32 v199, v199, v130
	v_add_f32_e32 v211, v211, v187
	s_waitcnt lgkmcnt(2)
	v_mfma_f32_32x32x16_bf16 v[96:111], v[216:219], v[120:123], v[96:111]
	v_add_f32_e32 v199, v199, v183
	v_add_f32_e32 v211, v211, v190
	v_cvt_pk_bf16_f32 v236, v210, v214
	ds_read_b128 v[240:243], v202 offset:8192
	v_add_f32_e32 v199, v199, v184
	v_add_f32_e32 v209, v211, v192
	v_cvt_pk_bf16_f32 v237, v207, v208
	v_add_f32_e32 v199, v199, v185
	v_add_f32_e32 v213, v209, v193
	s_waitcnt lgkmcnt(2)
	v_mfma_f32_32x32x16_bf16 v[80:95], v[222:225], v[120:123], v[80:95]
	ds_read_b128 v[208:211], v251 offset:49152
	v_add_f32_e32 v199, v199, v188
	v_add_f32_e32 v207, v213, v196
	s_waitcnt lgkmcnt(2)
	v_mfma_f32_32x32x16_bf16 v[96:111], v[226:229], v[124:127], v[96:111]
	v_add_f32_e32 v199, v199, v191
	v_add_f32_e32 v207, v207, v197
	v_cvt_pk_bf16_f32 v238, v205, v206
	ds_read_b128 v[224:227], v251 offset:53248
	v_add_f32_e32 v199, v199, v189
	v_add_f32_e32 v205, v207, v194
	v_cvt_pk_bf16_f32 v239, v204, v203
	v_add_f32_e32 v216, v199, v186
	v_add_f32_e32 v199, v205, v195
	s_waitcnt lgkmcnt(2)
	v_mfma_f32_32x32x16_bf16 v[80:95], v[240:243], v[124:127], v[80:95]
	s_waitcnt vmcnt(0)
	s_barrier
	s_waitcnt lgkmcnt(1)
	v_mfma_f32_32x32x16_bf16 v[64:79], v[208:211], v[232:235], v[64:79]
	s_add_i32 m0, s8, 0x10000
	ds_read_b128 v[204:207], v251 offset:57344
	global_load_lds_dwordx4 v140, s[98:99]
	v_exp_f32_e32 v217, v96
	v_exp_f32_e32 v219, v97
	v_cvt_pk_bf16_f32 v228, v130, v187
	s_waitcnt lgkmcnt(1)
	v_mfma_f32_32x32x16_bf16 v[48:63], v[224:227], v[232:235], v[48:63]
	ds_read_b128 v[240:243], v251 offset:61440
	v_exp_f32_e32 v218, v98
	v_exp_f32_e32 v222, v99
	v_cvt_pk_bf16_f32 v229, v183, v190
	s_waitcnt lgkmcnt(1)
	v_mfma_f32_32x32x16_bf16 v[32:47], v[204:207], v[232:235], v[32:47]
	s_add_i32 m0, m0, 0x4000
	ds_read_b128 v[96:99], v252 offset:49152
	global_load_lds_dwordx4 v144, s[100:101]
	v_exp_f32_e32 v211, v100
	v_exp_f32_e32 v215, v101
	v_cvt_pk_bf16_f32 v230, v184, v192
	s_waitcnt lgkmcnt(1)
	v_mfma_f32_32x32x16_bf16 v[16:31], v[240:243], v[232:235], v[16:31]
	ds_read_b128 v[224:227], v252 offset:53248
	v_exp_f32_e32 v209, v102
	v_exp_f32_e32 v213, v103
	v_cvt_pk_bf16_f32 v231, v185, v193
	s_waitcnt lgkmcnt(1)
	v_mfma_f32_32x32x16_bf16 v[64:79], v[96:99], v[236:239], v[64:79]
	s_add_i32 m0, m0, 0xffffc400
	ds_read_b128 v[100:103], v252 offset:57344
	global_load_lds_dwordx4 v142, s[98:99]
	v_exp_f32_e32 v210, v104
	v_exp_f32_e32 v214, v105
	v_cvt_pk_bf16_f32 v232, v188, v196
	s_waitcnt lgkmcnt(1)
	v_mfma_f32_32x32x16_bf16 v[48:63], v[224:227], v[236:239], v[48:63]
	ds_read_b128 v[96:99], v252 offset:61440
	v_exp_f32_e32 v207, v106
	v_exp_f32_e32 v208, v107
	v_cvt_pk_bf16_f32 v233, v191, v197
	s_waitcnt lgkmcnt(1)
	v_mfma_f32_32x32x16_bf16 v[32:47], v[100:103], v[236:239], v[32:47]
	s_add_i32 m0, m0, 0x4000
	ds_read_b128 v[104:107], v253 offset:49152
	global_load_lds_dwordx4 v146, s[100:101]
	s_add_u32 s98, s98, 0x20000
	s_addc_u32 s99, s99, 0
	s_add_u32 s100, s100, 0x80
	s_addc_u32 s101, s101, 0
	v_exp_f32_e32 v205, v108
	v_exp_f32_e32 v206, v109
	v_cvt_pk_bf16_f32 v234, v189, v194
	s_waitcnt lgkmcnt(1)
	v_mfma_f32_32x32x16_bf16 v[16:31], v[96:99], v[236:239], v[16:31]
	ds_read_b128 v[100:103], v253 offset:53248
	v_exp_f32_e32 v204, v110
	v_exp_f32_e32 v203, v111
	v_cvt_pk_bf16_f32 v235, v186, v195
	s_waitcnt lgkmcnt(1)
	v_mfma_f32_32x32x16_bf16 v[64:79], v[104:107], v[228:231], v[64:79]
	ds_read_b128 v[96:99], v253 offset:57344
	v_exp_f32_e32 v130, v80
	v_exp_f32_e32 v187, v81
	s_waitcnt lgkmcnt(1)
	v_mfma_f32_32x32x16_bf16 v[48:63], v[100:103], v[228:231], v[48:63]
	ds_read_b128 v[104:107], v253 offset:61440
	v_exp_f32_e32 v183, v82
	v_exp_f32_e32 v190, v83
	s_waitcnt lgkmcnt(1)
	v_mfma_f32_32x32x16_bf16 v[32:47], v[96:99], v[228:231], v[32:47]
	ds_read_b128 v[80:83], v254 offset:49152
	v_exp_f32_e32 v184, v84
	v_exp_f32_e32 v192, v85
	s_waitcnt lgkmcnt(1)
	v_mfma_f32_32x32x16_bf16 v[16:31], v[104:107], v[228:231], v[16:31]
	ds_read_b128 v[96:99], v254 offset:53248
	v_exp_f32_e32 v185, v86
	v_exp_f32_e32 v193, v87
	s_waitcnt lgkmcnt(1)
	v_mfma_f32_32x32x16_bf16 v[64:79], v[80:83], v[232:235], v[64:79]
	ds_read_b128 v[84:87], v254 offset:57344
	v_exp_f32_e32 v188, v88
	v_exp_f32_e32 v196, v89
	s_waitcnt lgkmcnt(1)
	v_mfma_f32_32x32x16_bf16 v[48:63], v[96:99], v[232:235], v[48:63]
	ds_read_b128 v[80:83], v254 offset:61440
	v_exp_f32_e32 v191, v90
	v_exp_f32_e32 v197, v91
	s_waitcnt lgkmcnt(1)
	v_mfma_f32_32x32x16_bf16 v[32:47], v[84:87], v[232:235], v[32:47]
	v_exp_f32_e32 v189, v92
	v_exp_f32_e32 v194, v93
	s_waitcnt lgkmcnt(0)
	v_mfma_f32_32x32x16_bf16 v[16:31], v[80:83], v[232:235], v[16:31]
	v_exp_f32_e32 v186, v94
	v_exp_f32_e32 v195, v95
	s_waitcnt lgkmcnt(0)
	s_add_i32 s33, s33, 1
	s_branch .Lattn_c1
.Lattn_exit:
	s_mov_b32 s34, 0x18000

; #define LAS __attribute__((address_space(3)))
; __global__ void __launch_bounds__(512, 2) fwd_kernel(Args args) {
;     extern __shared__ __attribute__((aligned(16))) unsigned char lds_raw[];
;     LAS unsigned char* lds = (LAS unsigned char*)lds_raw;
;     cg::grid_group grid = cg::this_grid();
;     const int tid = threadIdx.x, lane = tid & 63, wave = __builtin_amdgcn_readfirstlane(tid >> 6);
;     const int G = gridDim.x, bx = blockIdx.x;
;     const int gw = bx * 8 + wave, NGW = G * 8;
	.amdhsa_kernel _Z10fwd_kernel4Args
		.amdhsa_group_segment_fixed_size 0
		.amdhsa_private_segment_fixed_size 0
		.amdhsa_kernarg_size 440
		.amdhsa_user_sgpr_count 2
		.amdhsa_user_sgpr_dispatch_ptr 0
		.amdhsa_user_sgpr_queue_ptr 0
		.amdhsa_user_sgpr_kernarg_segment_ptr 1
		.amdhsa_user_sgpr_dispatch_id 0
		.amdhsa_user_sgpr_kernarg_preload_length 0
		.amdhsa_user_sgpr_kernarg_preload_offset 0
		.amdhsa_user_sgpr_private_segment_size 0
		.amdhsa_uses_dynamic_stack 0
		.amdhsa_enable_private_segment 0
		.amdhsa_system_sgpr_workgroup_id_x 1
		.amdhsa_system_sgpr_workgroup_id_y 0
		.amdhsa_system_sgpr_workgroup_id_z 0
		.amdhsa_system_sgpr_workgroup_info 0
		.amdhsa_system_vgpr_workitem_id 2
		.amdhsa_next_free_vgpr 255
		.amdhsa_next_free_sgpr 102
		.amdhsa_accum_offset 256
		.amdhsa_reserve_vcc 1
		.amdhsa_float_round_mode_32 0
		.amdhsa_float_round_mode_16_64 0
		.amdhsa_float_denorm_mode_32 3
		.amdhsa_float_denorm_mode_16_64 3
		.amdhsa_dx10_clamp 1
		.amdhsa_ieee_mode 1
		.amdhsa_fp16_overflow 0
		.amdhsa_tg_split 0
		.amdhsa_exception_fp_ieee_invalid_op 0
		.amdhsa_exception_fp_denorm_src 0
		.amdhsa_exception_fp_ieee_div_zero 0
		.amdhsa_exception_fp_ieee_overflow 0
		.amdhsa_exception_fp_ieee_underflow 0
		.amdhsa_exception_fp_ieee_inexact 0
		.amdhsa_exception_int_div_zero 0
	.end_amdhsa_kernel

; #define LAS __attribute__((address_space(3)))
; __global__ void __launch_bounds__(512, 2) fwd_kernel(Args args) {
;     extern __shared__ __attribute__((aligned(16))) unsigned char lds_raw[];
;     LAS unsigned char* lds = (LAS unsigned char*)lds_raw;
;     cg::grid_group grid = cg::this_grid();
;     const int tid = threadIdx.x, lane = tid & 63, wave = __builtin_amdgcn_readfirstlane(tid >> 6);
;     const int G = gridDim.x, bx = blockIdx.x;
;     const int gw = bx * 8 + wave, NGW = G * 8;
amdhsa.kernels:
  - .agpr_count:     0
    .args:
      - .offset:         0
        .size:           184
        .value_kind:     by_value
      - .offset:         184
        .size:           4
        .value_kind:     hidden_block_count_x
      - .offset:         188
        .size:           4
        .value_kind:     hidden_block_count_y
      - .offset:         192
        .size:           4
        .value_kind:     hidden_block_count_z
      - .offset:         196
        .size:           2
        .value_kind:     hidden_group_size_x
      - .offset:         198
        .size:           2
        .value_kind:     hidden_group_size_y
      - .offset:         200
        .size:           2
        .value_kind:     hidden_group_size_z
      - .offset:         202
        .size:           2
        .value_kind:     hidden_remainder_x
      - .offset:         204
        .size:           2
        .value_kind:     hidden_remainder_y
      - .offset:         206
        .size:           2
        .value_kind:     hidden_remainder_z
      - .offset:         224
        .size:           8
        .value_kind:     hidden_global_offset_x
      - .offset:         232
        .size:           8
        .value_kind:     hidden_global_offset_y
      - .offset:         240
        .size:           8
        .value_kind:     hidden_global_offset_z
      - .offset:         248
        .size:           2
        .value_kind:     hidden_grid_dims
      - .offset:         272
        .size:           8
        .value_kind:     hidden_multigrid_sync_arg
      - .offset:         304
        .size:           4
        .value_kind:     hidden_dynamic_lds_size
    .group_segment_fixed_size: 0
    .kernarg_segment_align: 8
    .kernarg_segment_size: 440
    .language:       OpenCL C
    .language_version:
      - 2
      - 0
    .max_flat_workgroup_size: 512
    .name:           _Z10fwd_kernel4Args
    .private_segment_fixed_size: 0
    .sgpr_count:     108
    .sgpr_spill_count: 7
    .symbol:         _Z10fwd_kernel4Args.kd
    .uniform_work_group_size: 1
    .uses_dynamic_stack: false
    .vgpr_count:     255
    .vgpr_spill_count: 0
    .wavefront_size: 64
